# attention work queues: a wave's first unit is its rank in the queue (no atomic), later pops add 256, on top of v29
# speedup vs baseline: 1.0094x; 1.0060x over previous
.LBB0_346:
	s_or_b64 exec, exec, s[4:5]
	s_xor_b64 s[46:47], s[0:1], -1
	s_lshl_b32 s0, s48, 9
	v_readlane_b32 s1, v254, 57
	s_or_b32 s76, s0, s1
	v_mov_b32_e32 v0, v236
	s_mov_b64 s[0:1], s[38:39]
	s_waitcnt lgkmcnt(0)
	s_barrier
	s_load_dwordx2 s[4:5], s[0:1], 0x80
	v_readfirstlane_b32 s3, v0
	s_lshl_b32 s3, s3, 8
	s_and_b32 s3, s3, 0xffffc000
	s_add_i32 s49, s3, 0
	s_lshl_b64 s[6:7], s[76:77], 2
	s_waitcnt lgkmcnt(0)
	s_add_u32 s3, s4, s6
	s_addc_u32 s4, s5, s7
	v_readlane_b32 s5, v254, 27
	v_and_b32_e32 v246, 63, v0
	s_add_u32 s40, s3, s5
	s_addc_u32 s41, s4, 0
	v_cmp_eq_u32_e64 s[18:19], 0, v246
	v_readfirstlane_b32 s99, v236
	s_lshr_b32 s99, s99, 6
	s_and_b32 s100, s2, 0xfffffff8
	s_add_i32 s99, s99, s100
	s_branch .LBB0_350

.LBB0_350:
	s_cmp_lt_i32 s99, 0
	s_cbranch_scc1 .Lq_pop
	v_mov_b32_e32 v0, s99
	s_mov_b32 s99, -1
	s_branch .Lq_have

.LBB0_353:
	s_or_b64 exec, exec, s[6:7]
	s_waitcnt vmcnt(0)
	v_readfirstlane_b32 s3, v2
	s_nop 1
	v_add_u32_e32 v0, s3, v0
	v_add_u32_e32 v0, 0x100, v0

.Lq_have:
	v_readfirstlane_b32 s6, v0
	s_cmpk_gt_i32 s6, 0x31f
	s_mov_b64 s[4:5], -1
	s_cbranch_scc1 .LBB0_349
	s_cmpk_gt_i32 s6, 0x11f
	s_cbranch_scc0 .LBB0_361
	s_cmpk_gt_u32 s6, 0x19f
	s_cbranch_scc0 .LBB0_358
	s_add_i32 s3, s6, 0xfffffe60
	s_lshr_b32 s4, s3, 3
	s_and_b32 s4, s4, 0x3fffff8
	s_or_b32 s4, s4, s89
	s_lshl_b32 s4, s4, 6
	s_and_b32 s3, s3, 63
	s_or_b32 s3, s4, s3
	s_addk_i32 s3, 0xd00
	s_mov_b64 s[4:5], 0
